# v31 + code placement: the four attention flash-loop heads aligned to 64 bytes
# speedup vs baseline: 1.0003x; 1.0003x over previous
; #define DMA_K(T, SL) do { const long t_ = (long)(T) * (KVBLK * LDK); GLDS(ks0 + t_, (lds_uptr)((__attribute__((address_space(3))) char*)kdst + (SL))); \
;     if constexpr (DK == 128) GLDS(ks1 + t_, (lds_uptr)((__attribute__((address_space(3))) char*)kdst + (SL) + 8192)); } while (0)
; #define DMA_V(T, SL) do { const long t_ = (long)(T) * (KVBLK * LDK); GLDS(vs0 + t_, (lds_uptr)((__attribute__((address_space(3))) char*)vdst + (SL))); \
;     GLDS(vs1 + t_, (lds_uptr)((__attribute__((address_space(3))) char*)vdst + (SL) + 8192)); } while (0)
; #define WBAR(N) asm volatile("s_waitcnt vmcnt(" #N ") lgkmcnt(0)\n\ts_barrier" ::: "memory")
; #define PSM(P0, P1, T, MN, AL) do { float cb_ = 0.f; \
;     if constexpr (BIAS) { const int k0_ = (T) * KVBLK; const int rmin_ = k0_ - (qlo + 31), rmax_ = k0_ + 63 - qlo; \
;       if (rmin_ >= 91) cb_ = b_pos; else if (rmax_ <= -91) cb_ = b_neg; \
;       else add_bias(P0, P1, tb, k0_ - (qlo + r32) + 256, hi); } \
;     partialSM<DK>(P0, P1, m_reg, MN, AL, cb_); } while (0)
; template <int DK, int LDK, bool BIAS, bool NOMAX> ...
;     ...
;   if constexpr (NOMAX) { TBIAS(pA0, pA1, 0); curb = cb_; alA = 1.f;
; #pragma unroll
;     for (int r = 0; r < 16; ++r) { pA0[r] = __builtin_amdgcn_exp2f(pA0[r]); pA1[r] = __builtin_amdgcn_exp2f(pA1[r]); }
;     float ps0 = 0.f;
; #pragma unroll
;     for (int r = 0; r < 16; ++r) ps0 += pA0[r] + pA1[r];
;     { auto rr = __builtin_amdgcn_permlane32_swap(__float_as_uint(ps0), __float_as_uint(ps0), false, false);
;       ps0 = __uint_as_float(rr[0]) + __uint_as_float(rr[1]); }
;     l_reg = ps0; }
;   else PSM(pA0, pA1, 0, mnA, alA);
;   DMA_K(3, 3 * SHM_K); DMA_V(1, SHM_V);
;   if constexpr (DK == 128) WBAR(4); else WBAR(3);
;   bf16x8 kf[2][2]; s16x4 vl[3], vh[3];
; #pragma unroll
;   for (int q = 0; q < 2; ++q) { const int cbq = (q * 16 + hi * 8) * 2;
;     if constexpr (DK == 128) { kf[q][0] = *reinterpret_cast<const bf16x8*>(K_lds + SHM_K + KSWZ128(r32, cbq)); kf[q][1] = *reinterpret_cast<const bf16x8*>(K_lds + SHM_K + KSWZ128(32 + r32, cbq)); }
;     else { kf[q][0] = *reinterpret_cast<const bf16x8*>(K_lds + SHM_K + KSWZ64(r32, cbq)); kf[q][1] = *reinterpret_cast<const bf16x8*>(K_lds + SHM_K + KSWZ64(32 + r32, cbq)); } }
;   int sp = 0, sj = SHM_V, sn = 2 * SHM_V;
.LBB0_219:
	s_or_b64 exec, exec, s[4:5]
	s_nop 5
	v_exp_f32_e32 v102, v8
	v_exp_f32_e32 v126, v9
	v_lshl_add_u64 v[8:9], v[36:37], 0, s[78:79]
	s_add_i32 m0, s3, 0xc000
	v_and_b32_e32 v52, 63, v0
	global_load_lds_dwordx4 v[8:9], off
	v_lshl_add_u64 v[8:9], v[38:39], 0, s[88:89]
	s_add_i32 m0, s62, 0x4000
	v_lshlrev_b32_e32 v54, 4, v52
	global_load_lds_dwordx4 v[8:9], off
	v_lshl_add_u64 v[8:9], v[34:35], 0, s[88:89]
	s_add_i32 m0, s62, 0x6000
	v_lshlrev_b32_e32 v0, 3, v52
	global_load_lds_dwordx4 v[8:9], off
	v_and_b32_e32 v54, 0xc0, v54
	v_lshlrev_b32_e32 v55, 1, v52
	v_and_or_b32 v54, v0, 24, v54
	v_and_b32_e32 v55, 32, v55
	v_and_b32_e32 v0, 0x100, v0
	v_exp_f32_e32 v96, v2
	v_exp_f32_e32 v80, v18
	v_or3_b32 v170, v54, v55, v0
	v_exp_f32_e32 v2, v3
	v_exp_f32_e32 v0, v19
	v_exp_f32_e32 v98, v4
	v_exp_f32_e32 v82, v20
	v_exp_f32_e32 v4, v5
	v_exp_f32_e32 v120, v21
	v_add_f32_e32 v3, v96, v80
	v_exp_f32_e32 v100, v6
	v_exp_f32_e32 v122, v7
	v_pk_add_f32 v[6:7], v[2:3], v[0:1]
	v_exp_f32_e32 v84, v22
	v_pk_add_f32 v[6:7], v[6:7], v[6:7] op_sel_hi:[0,1]
	v_exp_f32_e32 v124, v23
	v_add_f32_e32 v5, v98, v82
	v_mov_b32_e32 v121, v7
	v_pk_add_f32 v[6:7], v[4:5], v[120:121]
	v_exp_f32_e32 v86, v24
	v_pk_add_f32 v[6:7], v[6:7], v[6:7] op_sel_hi:[0,1]
	v_exp_f32_e32 v128, v25
	v_add_f32_e32 v123, v100, v84
	v_mov_b32_e32 v125, v7
	v_pk_add_f32 v[6:7], v[122:123], v[124:125]
	v_exp_f32_e32 v104, v10
	v_exp_f32_e32 v88, v26
	v_pk_add_f32 v[6:7], v[6:7], v[6:7] op_sel_hi:[0,1]
	v_exp_f32_e32 v130, v11
	v_exp_f32_e32 v132, v27
	v_add_f32_e32 v127, v102, v86
	v_mov_b32_e32 v129, v7
	v_pk_add_f32 v[6:7], v[126:127], v[128:129]
	v_exp_f32_e32 v106, v12
	v_exp_f32_e32 v90, v28
	v_pk_add_f32 v[6:7], v[6:7], v[6:7] op_sel_hi:[0,1]
	v_exp_f32_e32 v134, v13
	v_exp_f32_e32 v136, v29
	v_add_f32_e32 v131, v104, v88
	v_mov_b32_e32 v133, v7
	v_pk_add_f32 v[6:7], v[130:131], v[132:133]
	v_exp_f32_e32 v108, v14
	v_exp_f32_e32 v92, v30
	v_pk_add_f32 v[6:7], v[6:7], v[6:7] op_sel_hi:[0,1]
	v_exp_f32_e32 v138, v15
	v_exp_f32_e32 v140, v31
	v_add_f32_e32 v135, v106, v90
	v_mov_b32_e32 v137, v7
	v_pk_add_f32 v[6:7], v[134:135], v[136:137]
	v_exp_f32_e32 v110, v16
	v_exp_f32_e32 v94, v32
	v_pk_add_f32 v[6:7], v[6:7], v[6:7] op_sel_hi:[0,1]
	v_exp_f32_e32 v142, v17
	v_exp_f32_e32 v164, v33
	v_add_f32_e32 v139, v108, v92
	v_mov_b32_e32 v141, v7
	v_pk_add_f32 v[6:7], v[138:139], v[140:141]
	v_add_f32_e32 v143, v110, v94
	v_pk_add_f32 v[6:7], v[6:7], v[6:7] op_sel_hi:[0,1]
	v_mov_b32_e32 v165, v7
	v_pk_add_f32 v[6:7], v[142:143], v[164:165]
	v_or_b32_e32 v53, 32, v171
	v_pk_add_f32 v[6:7], v[6:7], v[6:7] op_sel:[0,1] op_sel_hi:[1,0]
	s_xor_b64 s[12:13], s[0:1], -1
	v_mov_b32_e32 v3, v6
	s_nop 1
	v_permlane32_swap_b32_e32 v6, v3
	s_and_b32 s0, s7, 0x3fffffc0
	s_waitcnt vmcnt(3) lgkmcnt(0)
	s_barrier
	v_add_f32_e32 v186, v6, v3
	v_xad_u32 v3, v53, v51, v49
	s_lshl_b32 s0, s0, 2
	ds_read_b128 v[6:9], v3 offset:20480
	ds_read_b128 v[10:13], v3 offset:16384
	v_xad_u32 v3, v171, v51, v49
	s_add_i32 s2, s0, 0
	ds_read_b128 v[112:115], v3 offset:20480
	ds_read_b128 v[116:119], v3 offset:16384
	v_add3_u32 v3, v47, v45, s58
	s_and_b32 s0, s7, 64
	v_lshl_or_b32 v3, v3, 10, s0
	v_lshlrev_b32_e32 v5, 5, v43
	s_add_i32 s19, s19, s18
	v_or3_b32 v14, v3, v5, v46
	v_add3_u32 v3, s19, v45, v44
	v_lshl_or_b32 v3, v3, 10, s0
	v_or3_b32 v16, v3, v5, v46
	v_add_lshl_u32 v3, v204, v40, 2
	v_sub_u32_e32 v3, v171, v3
	v_ashrrev_i32_e32 v17, 31, v16
	v_add_u32_e32 v211, s66, v3
	s_lshl_b32 s0, s6, 13
	v_lshlrev_b32_e32 v3, 10, v41
	v_lshlrev_b64 v[160:161], 1, v[16:17]
	v_or3_b32 v16, s0, v3, v42
	s_add_i32 s2, s2, 0x1c000
	v_ashrrev_i32_e32 v17, 31, v16
	v_mov_b32_e32 v30, v1
	v_mov_b32_e32 v31, v1
	s_add_i32 s52, 0, 0x10000
	v_or_b32_e32 v209, v48, v190
	v_or_b32_e32 v210, v50, v190
	v_cmp_gt_u32_e64 s[46:47], 32, v52
	v_lshl_add_u32 v188, v40, 2, s2
	v_ashrrev_i32_e32 v15, 31, v14
	v_lshl_add_u64 v[162:163], v[16:17], 1, s[14:15]
	v_mov_b32_e32 v16, v1
	v_mov_b32_e32 v17, v1
	v_mov_b32_e32 v18, v1
	v_mov_b32_e32 v19, v1
	v_mov_b32_e32 v20, v1
	v_mov_b32_e32 v21, v1
	v_mov_b32_e32 v22, v1
	v_mov_b32_e32 v23, v1
	v_mov_b32_e32 v24, v1
	v_mov_b32_e32 v25, v1
	v_mov_b32_e32 v26, v1
	v_mov_b32_e32 v27, v1
	v_mov_b32_e32 v28, v1
	v_mov_b32_e32 v29, v1
	v_mov_b64_e32 v[46:47], v[30:31]
	v_mov_b64_e32 v[62:63], v[30:31]
	v_mov_b64_e32 v[78:79], v[30:31]
	s_mov_b32 s63, 0x10000
	v_add_u32_e32 v187, s52, v170
	s_movk_i32 s96, 0x4000
	v_or_b32_e32 v207, v206, v190
	v_or_b32_e32 v208, v191, v190
	v_lshlrev_b64 v[14:15], 1, v[14:15]
	s_mov_b32 s58, 0x8000
	s_mov_b32 s4, 0
	s_mov_b32 s97, -1
	s_movk_i32 s7, 0x80
	s_mov_b64 s[0:1], s[8:9]
	v_mov_b64_e32 v[44:45], v[28:29]
	v_mov_b64_e32 v[42:43], v[26:27]
	v_mov_b64_e32 v[40:41], v[24:25]
	v_mov_b64_e32 v[38:39], v[22:23]
	v_mov_b64_e32 v[36:37], v[20:21]
	v_mov_b64_e32 v[34:35], v[18:19]
	v_mov_b64_e32 v[32:33], v[16:17]
	v_mov_b64_e32 v[60:61], v[28:29]
	v_mov_b64_e32 v[58:59], v[26:27]
	v_mov_b64_e32 v[56:57], v[24:25]
	v_mov_b64_e32 v[54:55], v[22:23]
	v_mov_b64_e32 v[52:53], v[20:21]
	v_mov_b64_e32 v[50:51], v[18:19]
	v_mov_b64_e32 v[48:49], v[16:17]
	v_mov_b64_e32 v[76:77], v[28:29]
	v_mov_b64_e32 v[74:75], v[26:27]
	v_mov_b64_e32 v[72:73], v[24:25]
	v_mov_b64_e32 v[70:71], v[22:23]
	v_mov_b64_e32 v[68:69], v[20:21]
	v_mov_b64_e32 v[66:67], v[18:19]
	v_mov_b64_e32 v[64:65], v[16:17]
	v_mov_b32_e32 v81, v0
	v_mov_b32_e32 v83, v120
	v_mov_b32_e32 v85, v124
	v_mov_b32_e32 v87, v128
	v_mov_b32_e32 v89, v132
	v_mov_b32_e32 v91, v136
	v_mov_b32_e32 v93, v140
	v_mov_b32_e32 v95, v164
	v_mov_b32_e32 v97, v2
	v_mov_b32_e32 v99, v4
	v_mov_b32_e32 v101, v122
	v_mov_b32_e32 v103, v126
	v_mov_b32_e32 v105, v130
	v_mov_b32_e32 v107, v134
	v_mov_b32_e32 v109, v138
	v_mov_b32_e32 v111, v142
	.p2align	6

; #define DMA_K(T, SL) do { const long t_ = (long)(T) * (KVBLK * LDK); GLDS(ks0 + t_, (lds_uptr)((__attribute__((address_space(3))) char*)kdst + (SL))); \
;     if constexpr (DK == 128) GLDS(ks1 + t_, (lds_uptr)((__attribute__((address_space(3))) char*)kdst + (SL) + 8192)); } while (0)
; #define DMA_V(T, SL) do { const long t_ = (long)(T) * (KVBLK * LDK); GLDS(vs0 + t_, (lds_uptr)((__attribute__((address_space(3))) char*)vdst + (SL))); \
;     GLDS(vs1 + t_, (lds_uptr)((__attribute__((address_space(3))) char*)vdst + (SL) + 8192)); } while (0)
; #define WBAR(N) asm volatile("s_waitcnt vmcnt(" #N ") lgkmcnt(0)\n\ts_barrier" ::: "memory")
; #define PSM(P0, P1, T, MN, AL) do { float cb_ = 0.f; \
;     if constexpr (BIAS) { const int k0_ = (T) * KVBLK; const int rmin_ = k0_ - (qlo + 31), rmax_ = k0_ + 63 - qlo; \
;       if (rmin_ >= 91) cb_ = b_pos; else if (rmax_ <= -91) cb_ = b_neg; \
;       else add_bias(P0, P1, tb, k0_ - (qlo + r32) + 256, hi); } \
;     partialSM<DK>(P0, P1, m_reg, MN, AL, cb_); } while (0)
; template <int DK, int LDK, bool BIAS, bool NOMAX> ...
;     ...
;   if constexpr (NOMAX) { TBIAS(pA0, pA1, 0); curb = cb_; alA = 1.f;
; #pragma unroll
;     for (int r = 0; r < 16; ++r) { pA0[r] = __builtin_amdgcn_exp2f(pA0[r]); pA1[r] = __builtin_amdgcn_exp2f(pA1[r]); }
;     float ps0 = 0.f;
; #pragma unroll
;     for (int r = 0; r < 16; ++r) ps0 += pA0[r] + pA1[r];
;     { auto rr = __builtin_amdgcn_permlane32_swap(__float_as_uint(ps0), __float_as_uint(ps0), false, false);
;       ps0 = __uint_as_float(rr[0]) + __uint_as_float(rr[1]); }
;     l_reg = ps0; }
;   else PSM(pA0, pA1, 0, mnA, alA);
;   DMA_K(3, 3 * SHM_K); DMA_V(1, SHM_V);
;   if constexpr (DK == 128) WBAR(4); else WBAR(3);
;   bf16x8 kf[2][2]; s16x4 vl[3], vh[3];
; #pragma unroll
;   for (int q = 0; q < 2; ++q) { const int cbq = (q * 16 + hi * 8) * 2;
;     if constexpr (DK == 128) { kf[q][0] = *reinterpret_cast<const bf16x8*>(K_lds + SHM_K + KSWZ128(r32, cbq)); kf[q][1] = *reinterpret_cast<const bf16x8*>(K_lds + SHM_K + KSWZ128(32 + r32, cbq)); }
;     else { kf[q][0] = *reinterpret_cast<const bf16x8*>(K_lds + SHM_K + KSWZ64(r32, cbq)); kf[q][1] = *reinterpret_cast<const bf16x8*>(K_lds + SHM_K + KSWZ64(32 + r32, cbq)); } }
;   int sp = 0, sj = SHM_V, sn = 2 * SHM_V;
.LBB0_312:
	s_or_b64 exec, exec, s[4:5]
	s_nop 5
	v_exp_f32_e32 v102, v8
	v_exp_f32_e32 v126, v9
	v_lshl_add_u64 v[8:9], v[36:37], 0, s[78:79]
	s_add_i32 m0, s3, 0xc000
	v_and_b32_e32 v52, 63, v0
	global_load_lds_dwordx4 v[8:9], off
	v_lshl_add_u64 v[8:9], v[38:39], 0, s[88:89]
	s_add_i32 m0, s62, 0x4000
	v_lshlrev_b32_e32 v54, 4, v52
	global_load_lds_dwordx4 v[8:9], off
	v_lshl_add_u64 v[8:9], v[34:35], 0, s[88:89]
	s_add_i32 m0, s62, 0x6000
	v_lshlrev_b32_e32 v0, 3, v52
	global_load_lds_dwordx4 v[8:9], off
	v_and_b32_e32 v54, 0xc0, v54
	v_lshlrev_b32_e32 v55, 1, v52
	v_and_or_b32 v54, v0, 24, v54
	v_and_b32_e32 v55, 32, v55
	v_and_b32_e32 v0, 0x100, v0
	v_exp_f32_e32 v96, v2
	v_exp_f32_e32 v80, v18
	v_or3_b32 v171, v54, v55, v0
	v_exp_f32_e32 v2, v3
	v_exp_f32_e32 v0, v19
	v_exp_f32_e32 v98, v4
	v_exp_f32_e32 v82, v20
	v_exp_f32_e32 v4, v5
	v_exp_f32_e32 v120, v21
	v_add_f32_e32 v3, v96, v80
	v_exp_f32_e32 v100, v6
	v_exp_f32_e32 v122, v7
	v_pk_add_f32 v[6:7], v[2:3], v[0:1]
	v_exp_f32_e32 v84, v22
	v_pk_add_f32 v[6:7], v[6:7], v[6:7] op_sel_hi:[0,1]
	v_exp_f32_e32 v124, v23
	v_add_f32_e32 v5, v98, v82
	v_mov_b32_e32 v121, v7
	v_pk_add_f32 v[6:7], v[4:5], v[120:121]
	v_exp_f32_e32 v86, v24
	v_pk_add_f32 v[6:7], v[6:7], v[6:7] op_sel_hi:[0,1]
	v_exp_f32_e32 v128, v25
	v_add_f32_e32 v123, v100, v84
	v_mov_b32_e32 v125, v7
	v_pk_add_f32 v[6:7], v[122:123], v[124:125]
	v_exp_f32_e32 v104, v10
	v_exp_f32_e32 v88, v26
	v_pk_add_f32 v[6:7], v[6:7], v[6:7] op_sel_hi:[0,1]
	v_exp_f32_e32 v130, v11
	v_exp_f32_e32 v132, v27
	v_add_f32_e32 v127, v102, v86
	v_mov_b32_e32 v129, v7
	v_pk_add_f32 v[6:7], v[126:127], v[128:129]
	v_exp_f32_e32 v106, v12
	v_exp_f32_e32 v90, v28
	v_pk_add_f32 v[6:7], v[6:7], v[6:7] op_sel_hi:[0,1]
	v_exp_f32_e32 v134, v13
	v_exp_f32_e32 v136, v29
	v_add_f32_e32 v131, v104, v88
	v_mov_b32_e32 v133, v7
	v_pk_add_f32 v[6:7], v[130:131], v[132:133]
	v_exp_f32_e32 v108, v14
	v_exp_f32_e32 v92, v30
	v_pk_add_f32 v[6:7], v[6:7], v[6:7] op_sel_hi:[0,1]
	v_exp_f32_e32 v138, v15
	v_exp_f32_e32 v140, v31
	v_add_f32_e32 v135, v106, v90
	v_mov_b32_e32 v137, v7
	v_pk_add_f32 v[6:7], v[134:135], v[136:137]
	v_exp_f32_e32 v110, v16
	v_exp_f32_e32 v94, v32
	v_pk_add_f32 v[6:7], v[6:7], v[6:7] op_sel_hi:[0,1]
	v_exp_f32_e32 v142, v17
	v_exp_f32_e32 v164, v33
	v_add_f32_e32 v139, v108, v92
	v_mov_b32_e32 v141, v7
	v_pk_add_f32 v[6:7], v[138:139], v[140:141]
	v_add_f32_e32 v143, v110, v94
	v_pk_add_f32 v[6:7], v[6:7], v[6:7] op_sel_hi:[0,1]
	v_mov_b32_e32 v165, v7
	v_pk_add_f32 v[6:7], v[142:143], v[164:165]
	v_or_b32_e32 v53, 32, v170
	v_pk_add_f32 v[6:7], v[6:7], v[6:7] op_sel:[0,1] op_sel_hi:[1,0]
	s_xor_b64 s[10:11], s[0:1], -1
	v_mov_b32_e32 v3, v6
	s_nop 1
	v_permlane32_swap_b32_e32 v6, v3
	s_and_b32 s0, s17, 0x3fffffc0
	s_waitcnt vmcnt(3) lgkmcnt(0)
	s_barrier
	v_add_f32_e32 v186, v6, v3
	v_xad_u32 v3, v53, v51, v49
	s_lshl_b32 s0, s0, 2
	ds_read_b128 v[6:9], v3 offset:20480
	ds_read_b128 v[10:13], v3 offset:16384
	v_xad_u32 v3, v170, v51, v49
	s_add_i32 s2, s0, 0
	ds_read_b128 v[112:115], v3 offset:20480
	ds_read_b128 v[116:119], v3 offset:16384
	v_add3_u32 v3, v47, v45, s58
	s_and_b32 s0, s17, 64
	v_lshl_or_b32 v3, v3, 10, s0
	v_lshlrev_b32_e32 v5, 5, v43
	s_add_i32 s19, s19, s18
	v_or3_b32 v14, v3, v5, v46
	v_add3_u32 v3, s19, v45, v44
	v_lshl_or_b32 v3, v3, 10, s0
	v_or3_b32 v16, v3, v5, v46
	v_add_lshl_u32 v3, v204, v40, 2
	v_sub_u32_e32 v3, v170, v3
	v_ashrrev_i32_e32 v17, 31, v16
	v_add_u32_e32 v211, s66, v3
	s_lshl_b32 s0, s16, 13
	v_lshlrev_b32_e32 v3, 10, v41
	v_lshlrev_b64 v[160:161], 1, v[16:17]
	v_or3_b32 v16, s0, v3, v42
	s_add_i32 s2, s2, 0x1c000
	v_ashrrev_i32_e32 v17, 31, v16
	v_mov_b32_e32 v30, v1
	v_mov_b32_e32 v31, v1
	s_add_i32 s52, 0, 0x10000
	v_or_b32_e32 v209, v48, v190
	v_or_b32_e32 v210, v50, v190
	v_cmp_gt_u32_e64 s[46:47], 32, v52
	v_lshl_add_u32 v188, v40, 2, s2
	v_ashrrev_i32_e32 v15, 31, v14
	v_lshl_add_u64 v[162:163], v[16:17], 1, s[12:13]
	v_mov_b32_e32 v16, v1
	v_mov_b32_e32 v17, v1
	v_mov_b32_e32 v18, v1
	v_mov_b32_e32 v19, v1
	v_mov_b32_e32 v20, v1
	v_mov_b32_e32 v21, v1
	v_mov_b32_e32 v22, v1
	v_mov_b32_e32 v23, v1
	v_mov_b32_e32 v24, v1
	v_mov_b32_e32 v25, v1
	v_mov_b32_e32 v26, v1
	v_mov_b32_e32 v27, v1
	v_mov_b32_e32 v28, v1
	v_mov_b32_e32 v29, v1
	v_mov_b64_e32 v[46:47], v[30:31]
	v_mov_b64_e32 v[62:63], v[30:31]
	v_mov_b64_e32 v[78:79], v[30:31]
	s_mov_b32 s63, 0x10000
	v_add_u32_e32 v187, s52, v171
	s_movk_i32 s95, 0x4000
	v_or_b32_e32 v207, v206, v190
	v_or_b32_e32 v208, v191, v190
	v_lshlrev_b64 v[14:15], 1, v[14:15]
	s_mov_b32 s97, 0x8000
	s_mov_b32 s4, 0
	s_mov_b32 s96, -1
	s_movk_i32 s94, 0x80
	s_mov_b64 s[0:1], s[6:7]
	v_mov_b64_e32 v[44:45], v[28:29]
	v_mov_b64_e32 v[42:43], v[26:27]
	v_mov_b64_e32 v[40:41], v[24:25]
	v_mov_b64_e32 v[38:39], v[22:23]
	v_mov_b64_e32 v[36:37], v[20:21]
	v_mov_b64_e32 v[34:35], v[18:19]
	v_mov_b64_e32 v[32:33], v[16:17]
	v_mov_b64_e32 v[60:61], v[28:29]
	v_mov_b64_e32 v[58:59], v[26:27]
	v_mov_b64_e32 v[56:57], v[24:25]
	v_mov_b64_e32 v[54:55], v[22:23]
	v_mov_b64_e32 v[52:53], v[20:21]
	v_mov_b64_e32 v[50:51], v[18:19]
	v_mov_b64_e32 v[48:49], v[16:17]
	v_mov_b64_e32 v[76:77], v[28:29]
	v_mov_b64_e32 v[74:75], v[26:27]
	v_mov_b64_e32 v[72:73], v[24:25]
	v_mov_b64_e32 v[70:71], v[22:23]
	v_mov_b64_e32 v[68:69], v[20:21]
	v_mov_b64_e32 v[66:67], v[18:19]
	v_mov_b64_e32 v[64:65], v[16:17]
	v_mov_b32_e32 v81, v0
	v_mov_b32_e32 v83, v120
	v_mov_b32_e32 v85, v124
	v_mov_b32_e32 v87, v128
	v_mov_b32_e32 v89, v132
	v_mov_b32_e32 v91, v136
	v_mov_b32_e32 v93, v140
	v_mov_b32_e32 v95, v164
	v_mov_b32_e32 v97, v2
	v_mov_b32_e32 v99, v4
	v_mov_b32_e32 v101, v122
	v_mov_b32_e32 v103, v126
	v_mov_b32_e32 v105, v130
	v_mov_b32_e32 v107, v134
	v_mov_b32_e32 v109, v138
	v_mov_b32_e32 v111, v142
	.p2align	6

; #define DMA_K(T, SL) do { const long t_ = (long)(T) * (KVBLK * LDK); GLDS(ks0 + t_, (lds_uptr)((__attribute__((address_space(3))) char*)kdst + (SL))); \
;     if constexpr (DK == 128) GLDS(ks1 + t_, (lds_uptr)((__attribute__((address_space(3))) char*)kdst + (SL) + 8192)); } while (0)
; #define DMA_V(T, SL) do { const long t_ = (long)(T) * (KVBLK * LDK); GLDS(vs0 + t_, (lds_uptr)((__attribute__((address_space(3))) char*)vdst + (SL))); \
;     GLDS(vs1 + t_, (lds_uptr)((__attribute__((address_space(3))) char*)vdst + (SL) + 8192)); } while (0)
; #define WBAR(N) asm volatile("s_waitcnt vmcnt(" #N ") lgkmcnt(0)\n\ts_barrier" ::: "memory")
; template <int DK>
; __device__ __forceinline__ void qkt(f32x16& p0, f32x16& p1, const char* Ks, const bf16x8* qr, int r32, int hi) {
;   p0 = f32x16{}; p1 = f32x16{};
; #pragma unroll
;   for (int d0 = 0; d0 < DK / 16; ++d0) { const int cb = (d0 * 16 + hi * 8) * 2;
;     bf16x8 b0, b1;
;     if constexpr (DK == 128) { b0 = *reinterpret_cast<const bf16x8*>(Ks + KSWZ128(r32, cb)); b1 = *reinterpret_cast<const bf16x8*>(Ks + KSWZ128(32 + r32, cb)); }
;     else { b0 = *reinterpret_cast<const bf16x8*>(Ks + KSWZ64(r32, cb)); b1 = *reinterpret_cast<const bf16x8*>(Ks + KSWZ64(32 + r32, cb)); }
;     p0 = __builtin_amdgcn_mfma_f32_32x32x16_bf16(b0, qr[d0], p0, 0, 0, 0);
;     p1 = __builtin_amdgcn_mfma_f32_32x32x16_bf16(b1, qr[d0], p1, 0, 0, 0); }
; template <int DK, int LDK, bool BIAS, bool NOMAX> ...
;     ...
;   WBAR(0);
;   DMA_K(0, 0); DMA_V(0, 0); DMA_K(1, SHM_K); DMA_K(2, 2 * SHM_K);
;   if constexpr (DK == 128) WBAR(6); else WBAR(4);
;   qkt<DK>(pA0, pA1, K_lds, qr, r32, hi);
;   if constexpr (NOMAX) { TBIAS(pA0, pA1, 0); curb = cb_; alA = 1.f;
; #pragma unroll
;     for (int r = 0; r < 16; ++r) { pA0[r] = __builtin_amdgcn_exp2f(pA0[r]); pA1[r] = __builtin_amdgcn_exp2f(pA1[r]); }
;     float ps0 = 0.f;
; #pragma unroll
;     for (int r = 0; r < 16; ++r) ps0 += pA0[r] + pA1[r];
;     { auto rr = __builtin_amdgcn_permlane32_swap(__float_as_uint(ps0), __float_as_uint(ps0), false, false);
;       ps0 = __uint_as_float(rr[0]) + __uint_as_float(rr[1]); }
;     l_reg = ps0; }
;   else PSM(pA0, pA1, 0, mnA, alA);
;   DMA_K(3, 3 * SHM_K); DMA_V(1, SHM_V);
;   if constexpr (DK == 128) WBAR(4); else WBAR(3);
.LBB0_401:
	s_or_b64 exec, exec, s[0:1]
	s_and_b32 s0, s20, 0xffffe000
	s_lshr_b32 s3, s21, 5
	s_addk_i32 s0, 0x4000
	s_ashr_i32 s1, s0, 31
	s_and_b32 s3, s3, 4
	s_lshl_b64 s[0:1], s[0:1], 9
	s_lshl_b32 s3, s3, 6
	s_or_b32 s0, s0, s3
	s_add_u32 s42, s86, s0
	s_addc_u32 s43, s87, s1
	s_ashr_i32 s41, s40, 31
	s_lshl_b64 s[0:1], s[40:41], 9
	v_readlane_b32 s4, v249, 44
	v_readlane_b32 s5, v249, 45
	s_add_u32 s3, s4, s0
	s_addc_u32 s7, s5, s1
	v_readlane_b32 s4, v249, 42
	v_readlane_b32 s5, v249, 43
	s_add_u32 s0, s4, s0
	s_addc_u32 s1, s5, s1
	s_lshl_b32 s2, s2, 6
	s_and_b32 s2, s2, 0x100
	s_add_u32 s4, s0, s2
	s_addc_u32 s5, s1, 0
	v_mov_b32_e32 v50, v176
	s_add_u32 s6, s3, s2
	s_addc_u32 s7, s7, 0
	v_readfirstlane_b32 s0, v50
	s_ashr_i32 s2, s0, 6
	v_bfe_u32 v51, v50, 4, 2
	v_lshl_or_b32 v2, s2, 2, v51
	v_and_b32_e32 v3, 15, v50
	s_add_i32 s1, s2, 8
	v_and_b32_e32 v0, 31, v50
	v_bitop3_b32 v4, v2, v3, 15 bitop3:0x6c
	s_lshl_b32 s3, s1, 2
	s_ashr_i32 s10, s0, 4
	v_lshlrev_b32_e32 v52, 3, v4
	v_or_b32_e32 v4, s3, v51
	s_and_b32 s9, s10, -16
	v_bfe_u32 v54, v0, 2, 2
	v_lshrrev_b32_e32 v6, 1, v50
	s_lshr_b32 s10, s10, 1
	v_bfe_u32 v10, v50, 5, 1
	v_bitop3_b32 v3, v4, v3, 15 bitop3:0x6c
	s_lshl_b32 s8, s2, 1
	v_or_b32_e32 v5, s9, v54
	v_and_b32_e32 v55, 8, v6
	s_and_b32 s10, s10, 4
	v_lshlrev_b32_e32 v53, 3, v3
	v_bfe_u32 v3, v50, 2, 3
	v_or3_b32 v5, v5, s10, v55
	v_and_or_b32 v6, s8, 2, v10
	v_lshlrev_b32_e32 v7, 3, v50
	s_lshl_b32 s8, s1, 1
	v_lshlrev_b32_e32 v5, 8, v5
	v_lshlrev_b32_e32 v6, 5, v6
	v_and_b32_e32 v56, 24, v7
	v_bitop3_b32 v57, s3, -13, v3 bitop3:0xc8
	s_and_b32 s12, s8, 4
	v_or3_b32 v6, v5, v6, v56
	v_or3_b32 v3, v57, s12, v55
	v_and_or_b32 v5, s8, 2, v10
	v_lshl_or_b32 v2, v2, 8, v52
	v_lshlrev_b32_e32 v3, 8, v3
	v_lshlrev_b32_e32 v5, 5, v5
	s_lshl_b32 s11, s2, 10
	v_lshl_or_b32 v4, v4, 8, v53
	v_or3_b32 v8, v3, v5, v56
	v_ashrrev_i32_e32 v3, 31, v2
	s_add_i32 s2, s11, 0
	v_lshl_add_u64 v[40:41], v[2:3], 1, s[4:5]
	v_ashrrev_i32_e32 v5, 31, v4
	s_add_i32 s41, 0, 0x10000
	s_waitcnt vmcnt(0) lgkmcnt(0)
	s_barrier
	s_mov_b32 m0, s2
	v_lshl_add_u64 v[36:37], v[4:5], 1, s[4:5]
	v_ashrrev_i32_e32 v7, 31, v6
	s_add_i32 s3, s41, s11
	global_load_lds_dwordx4 v[40:41], off
	s_add_i32 m0, s2, 0x2000
	v_lshl_add_u64 v[38:39], v[6:7], 1, s[6:7]
	v_ashrrev_i32_e32 v9, 31, v8
	global_load_lds_dwordx4 v[36:37], off
	s_mov_b32 m0, s3
	v_lshl_add_u64 v[34:35], v[8:9], 1, s[6:7]
	global_load_lds_dwordx4 v[38:39], off
	s_add_i32 m0, s3, 0x2000
	s_mov_b64 s[16:17], 0x8000
	global_load_lds_dwordx4 v[34:35], off
	v_lshl_add_u64 v[2:3], v[40:41], 0, s[16:17]
	s_add_i32 m0, s2, 0x4000
	s_mov_b64 s[14:15], 0x10000
	global_load_lds_dwordx4 v[2:3], off
	v_lshl_add_u64 v[2:3], v[36:37], 0, s[16:17]
	s_add_i32 m0, s2, 0x6000
	v_lshlrev_b32_e32 v58, 4, v50
	global_load_lds_dwordx4 v[2:3], off
	v_lshl_add_u64 v[2:3], v[40:41], 0, s[14:15]
	s_add_i32 m0, s2, 0x8000
	v_lshlrev_b32_e32 v59, 4, v10
	global_load_lds_dwordx4 v[2:3], off
	v_lshl_add_u64 v[2:3], v[36:37], 0, s[14:15]
	s_add_i32 m0, s2, 0xa000
	v_lshlrev_b32_e32 v205, 8, v0
	global_load_lds_dwordx4 v[2:3], off
	v_add_u32_e32 v0, 0, v205
	v_and_b32_e32 v2, 0xf0, v58
	v_xor_b32_e32 v2, v59, v2
	s_waitcnt vmcnt(6) lgkmcnt(0)
	s_barrier
	v_add_u32_e32 v60, v0, v2
	ds_read_b128 v[2:5], v60
	ds_read_b128 v[18:21], v60 offset:8192
	s_waitcnt lgkmcnt(0)
	v_mfma_f32_32x32x16_bf16 v[2:17], v[2:5], v[158:161], 0
	v_and_b32_e32 v61, 0xf0, v58
	v_bitop3_b32 v42, v59, v61, 32 bitop3:0x36
	v_add_u32_e32 v62, v0, v42
	ds_read_b128 v[42:45], v62
	ds_read_b128 v[46:49], v62 offset:8192
	v_bitop3_b32 v217, v59, v61, 64 bitop3:0x36
	v_add_u32_e32 v216, v0, v217
	v_bitop3_b32 v215, v59, v61, s91 bitop3:0x36
	v_mfma_f32_32x32x16_bf16 v[18:33], v[18:21], v[158:161], 0
	v_add_u32_e32 v214, v0, v215
	s_movk_i32 s8, 0x80
	v_bitop3_b32 v213, v59, v61, s8 bitop3:0x36
	v_add_u32_e32 v212, v0, v213
	s_movk_i32 s8, 0xa0
	v_bitop3_b32 v211, v59, v61, s8 bitop3:0x36
	v_add_u32_e32 v210, v0, v211
	s_waitcnt lgkmcnt(0)
	v_mfma_f32_32x32x16_bf16 v[2:17], v[42:45], v[154:157], v[2:17]
	s_movk_i32 s8, 0xc0
	v_bitop3_b32 v209, v59, v61, s8 bitop3:0x36
	v_add_u32_e32 v208, v0, v209
	s_movk_i32 s8, 0xe0
	v_and_b32_e32 v63, 63, v50
	v_bitop3_b32 v207, v59, v61, s8 bitop3:0x36
	v_lshlrev_b32_e32 v63, 3, v63
	v_mfma_f32_32x32x16_bf16 v[18:33], v[46:49], v[154:157], v[18:33]
	ds_read_b128 v[42:45], v216
	ds_read_b128 v[46:49], v216 offset:8192
	v_add_u32_e32 v206, v0, v207
	v_lshlrev_b32_e32 v0, 1, v50
	v_and_b32_e32 v0, 32, v0
	s_mov_b64 s[38:39], 0x18000
	s_add_i32 m0, s2, 0xc000
	s_and_b32 s1, s1, 1
	s_waitcnt lgkmcnt(0)
	v_mfma_f32_32x32x16_bf16 v[2:17], v[42:45], v[150:153], v[2:17]
	s_lshl_b32 s1, s1, 6
	s_and_b32 s0, s0, 64
	v_or_b32_e32 v64, 0xe0, v59
	s_movk_i32 s14, 0x4000
	s_mov_b32 s15, 1
	s_mov_b32 s18, 0x8000
	s_mov_b32 s8, 0
	v_mfma_f32_32x32x16_bf16 v[18:33], v[46:49], v[150:153], v[18:33]
	ds_read_b128 v[42:45], v214
	ds_read_b128 v[46:49], v214 offset:8192
	v_bitop3_b32 v223, v64, v205, v61 bitop3:0xde
	v_bitop3_b32 v224, v59, v205, v61 bitop3:0xde
	s_waitcnt lgkmcnt(0)
	v_mfma_f32_32x32x16_bf16 v[2:17], v[42:45], v[146:149], v[2:17]
	v_mfma_f32_32x32x16_bf16 v[18:33], v[46:49], v[146:149], v[18:33]
	ds_read_b128 v[42:45], v212
	ds_read_b128 v[46:49], v212 offset:8192
	s_waitcnt lgkmcnt(0)
	v_mfma_f32_32x32x16_bf16 v[2:17], v[42:45], v[142:145], v[2:17]
	v_mfma_f32_32x32x16_bf16 v[18:33], v[46:49], v[142:145], v[18:33]
	ds_read_b128 v[42:45], v210
	ds_read_b128 v[46:49], v210 offset:8192
	s_waitcnt lgkmcnt(0)
	v_mfma_f32_32x32x16_bf16 v[2:17], v[42:45], v[138:141], v[2:17]
	ds_read_b128 v[42:45], v208
	v_mfma_f32_32x32x16_bf16 v[18:33], v[46:49], v[138:141], v[18:33]
	ds_read_b128 v[46:49], v208 offset:8192
	s_waitcnt lgkmcnt(0)
; #define DMA_K(T, SL) do { const long t_ = (long)(T) * (KVBLK * LDK); GLDS(ks0 + t_, (lds_uptr)((__attribute__((address_space(3))) char*)kdst + (SL))); \
;     if constexpr (DK == 128) GLDS(ks1 + t_, (lds_uptr)((__attribute__((address_space(3))) char*)kdst + (SL) + 8192)); } while (0)
; #define DMA_V(T, SL) do { const long t_ = (long)(T) * (KVBLK * LDK); GLDS(vs0 + t_, (lds_uptr)((__attribute__((address_space(3))) char*)vdst + (SL))); \
;     GLDS(vs1 + t_, (lds_uptr)((__attribute__((address_space(3))) char*)vdst + (SL) + 8192)); } while (0)
; #define WBAR(N) asm volatile("s_waitcnt vmcnt(" #N ") lgkmcnt(0)\n\ts_barrier" ::: "memory")
; #define PSM(P0, P1, T, MN, AL) do { float cb_ = 0.f; \
;     if constexpr (BIAS) { const int k0_ = (T) * KVBLK; const int rmin_ = k0_ - (qlo + 31), rmax_ = k0_ + 63 - qlo; \
;       if (rmin_ >= 91) cb_ = b_pos; else if (rmax_ <= -91) cb_ = b_neg; \
;       else add_bias(P0, P1, tb, k0_ - (qlo + r32) + 256, hi); } \
;     partialSM<DK>(P0, P1, m_reg, MN, AL, cb_); } while (0)
; template <int DK, int LDK, bool BIAS, bool NOMAX> ...
;     ...
;   if constexpr (NOMAX) { TBIAS(pA0, pA1, 0); curb = cb_; alA = 1.f;
; #pragma unroll
;     for (int r = 0; r < 16; ++r) { pA0[r] = __builtin_amdgcn_exp2f(pA0[r]); pA1[r] = __builtin_amdgcn_exp2f(pA1[r]); }
;     float ps0 = 0.f;
; #pragma unroll
;     for (int r = 0; r < 16; ++r) ps0 += pA0[r] + pA1[r];
;     { auto rr = __builtin_amdgcn_permlane32_swap(__float_as_uint(ps0), __float_as_uint(ps0), false, false);
;       ps0 = __uint_as_float(rr[0]) + __uint_as_float(rr[1]); }
;     l_reg = ps0; }
;   else PSM(pA0, pA1, 0, mnA, alA);
;   DMA_K(3, 3 * SHM_K); DMA_V(1, SHM_V);
;   if constexpr (DK == 128) WBAR(4); else WBAR(3);
;   bf16x8 kf[2][2]; s16x4 vl[3], vh[3];
; #pragma unroll
;   for (int q = 0; q < 2; ++q) { const int cbq = (q * 16 + hi * 8) * 2;
;     if constexpr (DK == 128) { kf[q][0] = *reinterpret_cast<const bf16x8*>(K_lds + SHM_K + KSWZ128(r32, cbq)); kf[q][1] = *reinterpret_cast<const bf16x8*>(K_lds + SHM_K + KSWZ128(32 + r32, cbq)); }
;     else { kf[q][0] = *reinterpret_cast<const bf16x8*>(K_lds + SHM_K + KSWZ64(r32, cbq)); kf[q][1] = *reinterpret_cast<const bf16x8*>(K_lds + SHM_K + KSWZ64(32 + r32, cbq)); } }
;   int sp = 0, sj = SHM_V, sn = 2 * SHM_V;
	v_mfma_f32_32x32x16_bf16 v[2:17], v[42:45], v[130:133], v[2:17]
	v_and_b32_e32 v42, 0xc0, v58
	v_and_or_b32 v58, v63, 24, v42
	ds_read_b128 v[42:45], v206
	v_mfma_f32_32x32x16_bf16 v[18:33], v[46:49], v[130:133], v[18:33]
	v_and_b32_e32 v46, 0x100, v63
	v_or3_b32 v202, v58, v0, v46
	ds_read_b128 v[46:49], v206 offset:8192
	v_or_b32_e32 v58, 0xa0, v59
	v_or_b32_e32 v63, 0xc0, v59
	v_add_u32_e32 v204, s41, v202
	v_bitop3_b32 v221, v58, v205, v61 bitop3:0xde
	s_waitcnt lgkmcnt(0)
	v_mfma_f32_32x32x16_bf16 v[2:17], v[42:45], v[134:137], v[2:17]
	v_or_b32_e32 v42, 32, v59
	v_or_b32_e32 v43, 64, v59
	v_or_b32_e32 v44, 0x60, v59
	v_or_b32_e32 v45, 0x80, v59
	v_bitop3_b32 v218, v43, v205, v61 bitop3:0xde
	v_bitop3_b32 v219, v44, v205, v61 bitop3:0xde
	v_bitop3_b32 v220, v45, v205, v61 bitop3:0xde
	s_nop 4
	v_exp_f32_e32 v84, v4
	v_exp_f32_e32 v108, v5
	v_lshl_add_u64 v[4:5], v[40:41], 0, s[38:39]
	global_load_lds_dwordx4 v[4:5], off
	v_lshl_add_u64 v[4:5], v[36:37], 0, s[38:39]
	s_add_i32 m0, s2, 0xe000
	v_mfma_f32_32x32x16_bf16 v[18:33], v[46:49], v[134:137], v[18:33]
	global_load_lds_dwordx4 v[4:5], off
	v_lshl_add_u64 v[4:5], v[38:39], 0, s[16:17]
	s_add_i32 m0, s3, 0x4000
	v_exp_f32_e32 v82, v2
	global_load_lds_dwordx4 v[4:5], off
	v_lshl_add_u64 v[4:5], v[34:35], 0, s[16:17]
	s_add_i32 m0, s3, 0x6000
	s_nop 4
	v_exp_f32_e32 v66, v18
	global_load_lds_dwordx4 v[4:5], off
	v_exp_f32_e32 v106, v3
	v_exp_f32_e32 v0, v19
	v_exp_f32_e32 v68, v20
	v_exp_f32_e32 v110, v21
	v_add_f32_e32 v107, v82, v66
	v_pk_add_f32 v[2:3], v[106:107], v[0:1]
	v_exp_f32_e32 v86, v6
	v_exp_f32_e32 v70, v22
	v_pk_add_f32 v[2:3], v[2:3], v[2:3] op_sel_hi:[0,1]
	v_exp_f32_e32 v112, v7
	v_exp_f32_e32 v114, v23
	v_add_f32_e32 v109, v84, v68
	v_mov_b32_e32 v111, v3
	v_pk_add_f32 v[2:3], v[108:109], v[110:111]
	v_exp_f32_e32 v88, v8
	v_exp_f32_e32 v72, v24
	v_pk_add_f32 v[2:3], v[2:3], v[2:3] op_sel_hi:[0,1]
	v_exp_f32_e32 v116, v9
	v_exp_f32_e32 v118, v25
	v_add_f32_e32 v113, v86, v70
	v_mov_b32_e32 v115, v3
	v_pk_add_f32 v[2:3], v[112:113], v[114:115]
	v_exp_f32_e32 v90, v10
	v_exp_f32_e32 v74, v26
	v_pk_add_f32 v[2:3], v[2:3], v[2:3] op_sel_hi:[0,1]
	v_exp_f32_e32 v120, v11
	v_exp_f32_e32 v122, v27
	v_add_f32_e32 v117, v88, v72
	v_mov_b32_e32 v119, v3
	v_pk_add_f32 v[2:3], v[116:117], v[118:119]
	v_exp_f32_e32 v92, v12
	v_exp_f32_e32 v76, v28
	v_pk_add_f32 v[2:3], v[2:3], v[2:3] op_sel_hi:[0,1]
	v_exp_f32_e32 v124, v13
	v_exp_f32_e32 v126, v29
	v_add_f32_e32 v121, v90, v74
	v_mov_b32_e32 v123, v3
	v_pk_add_f32 v[2:3], v[120:121], v[122:123]
	v_exp_f32_e32 v94, v14
	v_exp_f32_e32 v78, v30
	v_pk_add_f32 v[2:3], v[2:3], v[2:3] op_sel_hi:[0,1]
	v_exp_f32_e32 v128, v15
	v_exp_f32_e32 v184, v31
	v_add_f32_e32 v125, v92, v76
	v_mov_b32_e32 v127, v3
	v_pk_add_f32 v[2:3], v[124:125], v[126:127]
	v_exp_f32_e32 v96, v16
	v_exp_f32_e32 v80, v32
	v_pk_add_f32 v[2:3], v[2:3], v[2:3] op_sel_hi:[0,1]
	v_exp_f32_e32 v186, v17
	v_exp_f32_e32 v188, v33
	v_add_f32_e32 v129, v94, v78
	v_mov_b32_e32 v185, v3
	v_pk_add_f32 v[2:3], v[128:129], v[184:185]
	v_add_f32_e32 v187, v96, v80
	v_pk_add_f32 v[2:3], v[2:3], v[2:3] op_sel_hi:[0,1]
	v_mov_b32_e32 v189, v3
	v_pk_add_f32 v[2:3], v[186:187], v[188:189]
	v_and_b32_e32 v4, 32, v50
	v_pk_add_f32 v[2:3], v[2:3], v[2:3] op_sel:[0,1] op_sel_hi:[1,0]
	s_waitcnt vmcnt(4) lgkmcnt(0)
	s_barrier
	ds_read_b128 v[162:165], v62 offset:24576
	ds_read_b128 v[166:169], v62 offset:16384
	ds_read_b128 v[98:101], v60 offset:24576
	ds_read_b128 v[102:105], v60 offset:16384
	v_mov_b32_e32 v3, v2
	s_nop 1
	v_permlane32_swap_b32_e32 v2, v3
	v_add_f32_e32 v203, v2, v3
	v_or3_b32 v2, v57, v55, s12
	v_lshl_or_b32 v2, v2, 8, s1
	v_or3_b32 v2, v2, v4, v56
	v_ashrrev_i32_e32 v3, 31, v2
	v_lshlrev_b64 v[170:171], 1, v[2:3]
	v_or_b32_e32 v2, s9, v55
	v_or3_b32 v2, v2, s10, v54
	v_lshl_or_b32 v2, v2, 8, s0
	v_or3_b32 v2, v2, v4, v56
	v_ashrrev_i32_e32 v3, 31, v2
	s_add_i32 s0, s11, 0x2000
	v_lshlrev_b32_e32 v4, 8, v51
	v_lshlrev_b64 v[172:173], 1, v[2:3]
	v_or3_b32 v2, s0, v4, v53
	v_ashrrev_i32_e32 v3, 31, v2
	v_lshlrev_b64 v[180:181], 1, v[2:3]
	v_or3_b32 v2, s11, v4, v52
	v_ashrrev_i32_e32 v3, 31, v2
	v_lshlrev_b64 v[182:183], 1, v[2:3]
	v_mov_b32_e32 v2, 0
	v_bitop3_b32 v222, v63, v205, v61 bitop3:0xde
	v_bitop3_b32 v225, v42, v205, v61 bitop3:0xde
	s_mov_b64 s[0:1], s[42:43]
	s_mov_b32 s16, 0x8000
	v_mov_b32_e32 v3, v2
	v_mov_b32_e32 v4, v2
	v_mov_b32_e32 v5, v2
	v_mov_b32_e32 v6, v2
	v_mov_b32_e32 v7, v2
	v_mov_b32_e32 v8, v2
	v_mov_b32_e32 v9, v2
	v_mov_b32_e32 v10, v2
	v_mov_b32_e32 v11, v2
	v_mov_b32_e32 v12, v2
	v_mov_b32_e32 v13, v2
	v_mov_b32_e32 v14, v2
	v_mov_b32_e32 v15, v2
	v_mov_b32_e32 v16, v2
	v_mov_b32_e32 v17, v2
	v_mov_b32_e32 v18, v2
	v_mov_b32_e32 v19, v2
	v_mov_b32_e32 v20, v2
	v_mov_b32_e32 v21, v2
	v_mov_b32_e32 v22, v2
	v_mov_b32_e32 v23, v2
	v_mov_b32_e32 v24, v2
	v_mov_b32_e32 v25, v2
	v_mov_b32_e32 v26, v2
	v_mov_b32_e32 v27, v2
	v_mov_b32_e32 v28, v2
	v_mov_b32_e32 v29, v2
	v_mov_b32_e32 v30, v2
	v_mov_b32_e32 v31, v2
	v_mov_b32_e32 v32, v2
	v_mov_b32_e32 v33, v2
	v_mov_b32_e32 v34, v2
	v_mov_b32_e32 v35, v2
	v_mov_b32_e32 v36, v2
	v_mov_b32_e32 v37, v2
	v_mov_b32_e32 v38, v2
	v_mov_b32_e32 v39, v2
	v_mov_b32_e32 v40, v2
	v_mov_b32_e32 v41, v2
	v_mov_b32_e32 v42, v2
	v_mov_b32_e32 v43, v2
	v_mov_b32_e32 v44, v2
	v_mov_b32_e32 v45, v2
	v_mov_b32_e32 v46, v2
	v_mov_b32_e32 v47, v2
	v_mov_b32_e32 v48, v2
	v_mov_b32_e32 v49, v2
	v_mov_b32_e32 v50, v2
	v_mov_b32_e32 v51, v2
	v_mov_b32_e32 v52, v2
	v_mov_b32_e32 v53, v2
	v_mov_b32_e32 v54, v2
	v_mov_b32_e32 v55, v2
	v_mov_b32_e32 v56, v2
	v_mov_b32_e32 v57, v2
	v_mov_b32_e32 v58, v2
	v_mov_b32_e32 v59, v2
	v_mov_b32_e32 v60, v2
	v_mov_b32_e32 v61, v2
	v_mov_b32_e32 v62, v2
	v_mov_b32_e32 v63, v2
	v_mov_b32_e32 v64, v2
	v_mov_b32_e32 v65, v2
	v_mov_b32_e32 v67, v0
	v_mov_b32_e32 v69, v110
	v_mov_b32_e32 v71, v114
	v_mov_b32_e32 v73, v118
	v_mov_b32_e32 v75, v122
	v_mov_b32_e32 v77, v126
	v_mov_b32_e32 v79, v184
	v_mov_b32_e32 v81, v188
	v_mov_b32_e32 v83, v106
	v_mov_b32_e32 v85, v108
	v_mov_b32_e32 v87, v112
	v_mov_b32_e32 v89, v116
	v_mov_b32_e32 v91, v120
	v_mov_b32_e32 v93, v124
	v_mov_b32_e32 v95, v128
	v_mov_b32_e32 v97, v186
	.p2align	6

; #define DMA_K(T, SL) do { const long t_ = (long)(T) * (KVBLK * LDK); GLDS(ks0 + t_, (lds_uptr)((__attribute__((address_space(3))) char*)kdst + (SL))); \
;     if constexpr (DK == 128) GLDS(ks1 + t_, (lds_uptr)((__attribute__((address_space(3))) char*)kdst + (SL) + 8192)); } while (0)
; #define DMA_V(T, SL) do { const long t_ = (long)(T) * (KVBLK * LDK); GLDS(vs0 + t_, (lds_uptr)((__attribute__((address_space(3))) char*)vdst + (SL))); \
;     GLDS(vs1 + t_, (lds_uptr)((__attribute__((address_space(3))) char*)vdst + (SL) + 8192)); } while (0)
; #define WBAR(N) asm volatile("s_waitcnt vmcnt(" #N ") lgkmcnt(0)\n\ts_barrier" ::: "memory")
; template <int DK>
; __device__ __forceinline__ void qkt(f32x16& p0, f32x16& p1, const char* Ks, const bf16x8* qr, int r32, int hi) {
;   p0 = f32x16{}; p1 = f32x16{};
; #pragma unroll
;   for (int d0 = 0; d0 < DK / 16; ++d0) { const int cb = (d0 * 16 + hi * 8) * 2;
;     bf16x8 b0, b1;
;     if constexpr (DK == 128) { b0 = *reinterpret_cast<const bf16x8*>(Ks + KSWZ128(r32, cb)); b1 = *reinterpret_cast<const bf16x8*>(Ks + KSWZ128(32 + r32, cb)); }
;     else { b0 = *reinterpret_cast<const bf16x8*>(Ks + KSWZ64(r32, cb)); b1 = *reinterpret_cast<const bf16x8*>(Ks + KSWZ64(32 + r32, cb)); }
;     p0 = __builtin_amdgcn_mfma_f32_32x32x16_bf16(b0, qr[d0], p0, 0, 0, 0);
;     p1 = __builtin_amdgcn_mfma_f32_32x32x16_bf16(b1, qr[d0], p1, 0, 0, 0); }
; template <int DK, int LDK, bool BIAS, bool NOMAX> ...
;     ...
;   WBAR(0);
;   DMA_K(0, 0); DMA_V(0, 0); DMA_K(1, SHM_K); DMA_K(2, 2 * SHM_K);
;   if constexpr (DK == 128) WBAR(6); else WBAR(4);
;   qkt<DK>(pA0, pA1, K_lds, qr, r32, hi);
;   if constexpr (NOMAX) { TBIAS(pA0, pA1, 0); curb = cb_; alA = 1.f;
; #pragma unroll
;     for (int r = 0; r < 16; ++r) { pA0[r] = __builtin_amdgcn_exp2f(pA0[r]); pA1[r] = __builtin_amdgcn_exp2f(pA1[r]); }
;     float ps0 = 0.f;
; #pragma unroll
;     for (int r = 0; r < 16; ++r) ps0 += pA0[r] + pA1[r];
;     { auto rr = __builtin_amdgcn_permlane32_swap(__float_as_uint(ps0), __float_as_uint(ps0), false, false);
;       ps0 = __uint_as_float(rr[0]) + __uint_as_float(rr[1]); }
;     l_reg = ps0; }
;   else PSM(pA0, pA1, 0, mnA, alA);
;   DMA_K(3, 3 * SHM_K); DMA_V(1, SHM_V);
;   if constexpr (DK == 128) WBAR(4); else WBAR(3);
.LBB0_461:
	s_or_b64 exec, exec, s[0:1]
	s_lshr_b32 s3, s21, 4
	s_and_b32 s0, s20, 0xfffff000
	s_ashr_i32 s1, s0, 31
	s_and_b32 s3, s3, 4
	s_lshl_b64 s[0:1], s[0:1], 9
	s_lshl_b32 s3, s3, 6
	s_or_b32 s0, s0, s3
	s_add_u32 s42, s86, s0
	s_addc_u32 s43, s87, s1
	s_ashr_i32 s41, s40, 31
	s_lshl_b64 s[0:1], s[40:41], 9
	v_readlane_b32 s4, v249, 44
	v_readlane_b32 s5, v249, 45
	s_add_u32 s3, s4, s0
	s_addc_u32 s7, s5, s1
	v_readlane_b32 s4, v249, 42
	v_readlane_b32 s5, v249, 43
	s_add_u32 s0, s4, s0
	s_addc_u32 s1, s5, s1
	s_lshl_b32 s2, s2, 6
	s_and_b32 s2, s2, 0x100
	s_add_u32 s4, s0, s2
	s_addc_u32 s5, s1, 0
	v_mov_b32_e32 v50, v176
	s_add_u32 s6, s3, s2
	s_addc_u32 s7, s7, 0
	v_readfirstlane_b32 s0, v50
	s_ashr_i32 s2, s0, 6
	v_bfe_u32 v51, v50, 4, 2
	v_lshl_or_b32 v2, s2, 2, v51
	v_and_b32_e32 v3, 15, v50
	s_add_i32 s1, s2, 8
	v_and_b32_e32 v0, 31, v50
	v_bitop3_b32 v4, v2, v3, 15 bitop3:0x6c
	s_lshl_b32 s3, s1, 2
	s_ashr_i32 s10, s0, 4
	v_lshlrev_b32_e32 v52, 3, v4
	v_or_b32_e32 v4, s3, v51
	s_and_b32 s9, s10, -16
	v_bfe_u32 v54, v0, 2, 2
	v_lshrrev_b32_e32 v6, 1, v50
	s_lshr_b32 s10, s10, 1
	v_bfe_u32 v10, v50, 5, 1
	v_bitop3_b32 v3, v4, v3, 15 bitop3:0x6c
	s_lshl_b32 s8, s2, 1
	v_or_b32_e32 v5, s9, v54
	v_and_b32_e32 v55, 8, v6
	s_and_b32 s10, s10, 4
	v_lshlrev_b32_e32 v53, 3, v3
	v_bfe_u32 v3, v50, 2, 3
	v_or3_b32 v5, v5, s10, v55
	v_and_or_b32 v6, s8, 2, v10
	v_lshlrev_b32_e32 v7, 3, v50
	s_lshl_b32 s8, s1, 1
	v_lshlrev_b32_e32 v5, 8, v5
	v_lshlrev_b32_e32 v6, 5, v6
	v_and_b32_e32 v56, 24, v7
	v_bitop3_b32 v57, s3, -13, v3 bitop3:0xc8
	s_and_b32 s12, s8, 4
	v_or3_b32 v6, v5, v6, v56
	v_or3_b32 v3, v57, s12, v55
	v_and_or_b32 v5, s8, 2, v10
	v_lshl_or_b32 v2, v2, 8, v52
	v_lshlrev_b32_e32 v3, 8, v3
	v_lshlrev_b32_e32 v5, 5, v5
	s_lshl_b32 s11, s2, 10
	v_lshl_or_b32 v4, v4, 8, v53
	v_or3_b32 v8, v3, v5, v56
	v_ashrrev_i32_e32 v3, 31, v2
	s_add_i32 s2, s11, 0
	v_lshl_add_u64 v[40:41], v[2:3], 1, s[4:5]
	v_ashrrev_i32_e32 v5, 31, v4
	s_add_i32 s41, 0, 0x10000
	s_waitcnt vmcnt(0) lgkmcnt(0)
	s_barrier
	s_mov_b32 m0, s2
	v_lshl_add_u64 v[36:37], v[4:5], 1, s[4:5]
	v_ashrrev_i32_e32 v7, 31, v6
	s_add_i32 s3, s41, s11
	global_load_lds_dwordx4 v[40:41], off
	s_add_i32 m0, s2, 0x2000
	v_lshl_add_u64 v[38:39], v[6:7], 1, s[6:7]
	v_ashrrev_i32_e32 v9, 31, v8
	global_load_lds_dwordx4 v[36:37], off
	s_mov_b32 m0, s3
	v_lshl_add_u64 v[34:35], v[8:9], 1, s[6:7]
	global_load_lds_dwordx4 v[38:39], off
	s_add_i32 m0, s3, 0x2000
	s_mov_b64 s[16:17], 0x8000
	global_load_lds_dwordx4 v[34:35], off
	v_lshl_add_u64 v[2:3], v[40:41], 0, s[16:17]
	s_add_i32 m0, s2, 0x4000
	s_mov_b64 s[14:15], 0x10000
	global_load_lds_dwordx4 v[2:3], off
	v_lshl_add_u64 v[2:3], v[36:37], 0, s[16:17]
	s_add_i32 m0, s2, 0x6000
	v_lshlrev_b32_e32 v58, 4, v50
	global_load_lds_dwordx4 v[2:3], off
	v_lshl_add_u64 v[2:3], v[40:41], 0, s[14:15]
	s_add_i32 m0, s2, 0x8000
	v_lshlrev_b32_e32 v59, 4, v10
	global_load_lds_dwordx4 v[2:3], off
	v_lshl_add_u64 v[2:3], v[36:37], 0, s[14:15]
	s_add_i32 m0, s2, 0xa000
	v_lshlrev_b32_e32 v205, 8, v0
	global_load_lds_dwordx4 v[2:3], off
	v_add_u32_e32 v0, 0, v205
	v_and_b32_e32 v2, 0xf0, v58
	v_xor_b32_e32 v2, v59, v2
	s_waitcnt vmcnt(6) lgkmcnt(0)
	s_barrier
	v_add_u32_e32 v60, v0, v2
	ds_read_b128 v[2:5], v60
	ds_read_b128 v[18:21], v60 offset:8192
	s_waitcnt lgkmcnt(0)
	v_mfma_f32_32x32x16_bf16 v[2:17], v[2:5], v[158:161], 0
	v_and_b32_e32 v61, 0xf0, v58
	v_bitop3_b32 v42, v59, v61, 32 bitop3:0x36
	v_add_u32_e32 v62, v0, v42
	ds_read_b128 v[42:45], v62
	ds_read_b128 v[46:49], v62 offset:8192
	v_bitop3_b32 v217, v59, v61, 64 bitop3:0x36
	v_add_u32_e32 v216, v0, v217
	v_bitop3_b32 v215, v59, v61, s91 bitop3:0x36
	v_mfma_f32_32x32x16_bf16 v[18:33], v[18:21], v[158:161], 0
	v_add_u32_e32 v214, v0, v215
	s_movk_i32 s8, 0x80
	v_bitop3_b32 v213, v59, v61, s8 bitop3:0x36
	v_add_u32_e32 v212, v0, v213
	s_movk_i32 s8, 0xa0
	v_bitop3_b32 v211, v59, v61, s8 bitop3:0x36
	v_add_u32_e32 v210, v0, v211
	s_waitcnt lgkmcnt(0)
	v_mfma_f32_32x32x16_bf16 v[2:17], v[42:45], v[154:157], v[2:17]
	s_movk_i32 s8, 0xc0
	v_bitop3_b32 v209, v59, v61, s8 bitop3:0x36
	v_add_u32_e32 v208, v0, v209
	s_movk_i32 s8, 0xe0
	v_and_b32_e32 v63, 63, v50
	v_bitop3_b32 v207, v59, v61, s8 bitop3:0x36
	v_lshlrev_b32_e32 v63, 3, v63
	v_mfma_f32_32x32x16_bf16 v[18:33], v[46:49], v[154:157], v[18:33]
	ds_read_b128 v[42:45], v216
	ds_read_b128 v[46:49], v216 offset:8192
	v_add_u32_e32 v206, v0, v207
	v_lshlrev_b32_e32 v64, 1, v50
	v_and_b32_e32 v0, 32, v64
	s_mov_b64 s[38:39], 0x18000
	s_add_i32 m0, s2, 0xc000
	s_and_b32 s1, s1, 1
	s_waitcnt lgkmcnt(0)
	v_mfma_f32_32x32x16_bf16 v[2:17], v[42:45], v[150:153], v[2:17]
	s_lshl_b32 s1, s1, 6
	s_and_b32 s0, s0, 64
	v_or_b32_e32 v64, 0xe0, v59
	s_mov_b32 s14, 1
	s_movk_i32 s15, 0x4000
	s_mov_b32 s18, 0x8000
	s_mov_b32 s8, 0
	v_mfma_f32_32x32x16_bf16 v[18:33], v[46:49], v[150:153], v[18:33]
	ds_read_b128 v[42:45], v214
	ds_read_b128 v[46:49], v214 offset:8192
	v_bitop3_b32 v223, v64, v205, v61 bitop3:0xde
	v_bitop3_b32 v224, v59, v205, v61 bitop3:0xde
	s_waitcnt lgkmcnt(0)
	v_mfma_f32_32x32x16_bf16 v[2:17], v[42:45], v[146:149], v[2:17]
	v_mfma_f32_32x32x16_bf16 v[18:33], v[46:49], v[146:149], v[18:33]
	ds_read_b128 v[42:45], v212
	ds_read_b128 v[46:49], v212 offset:8192
	s_waitcnt lgkmcnt(0)
	v_mfma_f32_32x32x16_bf16 v[2:17], v[42:45], v[142:145], v[2:17]
	v_mfma_f32_32x32x16_bf16 v[18:33], v[46:49], v[142:145], v[18:33]
	ds_read_b128 v[42:45], v210
	ds_read_b128 v[46:49], v210 offset:8192
	s_waitcnt lgkmcnt(0)
	v_mfma_f32_32x32x16_bf16 v[2:17], v[42:45], v[138:141], v[2:17]
	ds_read_b128 v[42:45], v208
	v_mfma_f32_32x32x16_bf16 v[18:33], v[46:49], v[138:141], v[18:33]
	ds_read_b128 v[46:49], v208 offset:8192
	s_waitcnt lgkmcnt(0)
; #define DMA_K(T, SL) do { const long t_ = (long)(T) * (KVBLK * LDK); GLDS(ks0 + t_, (lds_uptr)((__attribute__((address_space(3))) char*)kdst + (SL))); \
;     if constexpr (DK == 128) GLDS(ks1 + t_, (lds_uptr)((__attribute__((address_space(3))) char*)kdst + (SL) + 8192)); } while (0)
; #define DMA_V(T, SL) do { const long t_ = (long)(T) * (KVBLK * LDK); GLDS(vs0 + t_, (lds_uptr)((__attribute__((address_space(3))) char*)vdst + (SL))); \
;     GLDS(vs1 + t_, (lds_uptr)((__attribute__((address_space(3))) char*)vdst + (SL) + 8192)); } while (0)
; #define WBAR(N) asm volatile("s_waitcnt vmcnt(" #N ") lgkmcnt(0)\n\ts_barrier" ::: "memory")
; #define PSM(P0, P1, T, MN, AL) do { float cb_ = 0.f; \
;     if constexpr (BIAS) { const int k0_ = (T) * KVBLK; const int rmin_ = k0_ - (qlo + 31), rmax_ = k0_ + 63 - qlo; \
;       if (rmin_ >= 91) cb_ = b_pos; else if (rmax_ <= -91) cb_ = b_neg; \
;       else add_bias(P0, P1, tb, k0_ - (qlo + r32) + 256, hi); } \
;     partialSM<DK>(P0, P1, m_reg, MN, AL, cb_); } while (0)
; template <int DK, int LDK, bool BIAS, bool NOMAX> ...
;     ...
;   if constexpr (NOMAX) { TBIAS(pA0, pA1, 0); curb = cb_; alA = 1.f;
; #pragma unroll
;     for (int r = 0; r < 16; ++r) { pA0[r] = __builtin_amdgcn_exp2f(pA0[r]); pA1[r] = __builtin_amdgcn_exp2f(pA1[r]); }
;     float ps0 = 0.f;
; #pragma unroll
;     for (int r = 0; r < 16; ++r) ps0 += pA0[r] + pA1[r];
;     { auto rr = __builtin_amdgcn_permlane32_swap(__float_as_uint(ps0), __float_as_uint(ps0), false, false);
;       ps0 = __uint_as_float(rr[0]) + __uint_as_float(rr[1]); }
;     l_reg = ps0; }
;   else PSM(pA0, pA1, 0, mnA, alA);
;   DMA_K(3, 3 * SHM_K); DMA_V(1, SHM_V);
;   if constexpr (DK == 128) WBAR(4); else WBAR(3);
;   bf16x8 kf[2][2]; s16x4 vl[3], vh[3];
; #pragma unroll
;   for (int q = 0; q < 2; ++q) { const int cbq = (q * 16 + hi * 8) * 2;
;     if constexpr (DK == 128) { kf[q][0] = *reinterpret_cast<const bf16x8*>(K_lds + SHM_K + KSWZ128(r32, cbq)); kf[q][1] = *reinterpret_cast<const bf16x8*>(K_lds + SHM_K + KSWZ128(32 + r32, cbq)); }
;     else { kf[q][0] = *reinterpret_cast<const bf16x8*>(K_lds + SHM_K + KSWZ64(r32, cbq)); kf[q][1] = *reinterpret_cast<const bf16x8*>(K_lds + SHM_K + KSWZ64(32 + r32, cbq)); } }
;   int sp = 0, sj = SHM_V, sn = 2 * SHM_V;
	v_mfma_f32_32x32x16_bf16 v[2:17], v[42:45], v[130:133], v[2:17]
	v_and_b32_e32 v42, 0xc0, v58
	v_and_or_b32 v58, v63, 24, v42
	ds_read_b128 v[42:45], v206
	v_mfma_f32_32x32x16_bf16 v[18:33], v[46:49], v[130:133], v[18:33]
	v_and_b32_e32 v46, 0x100, v63
	v_or3_b32 v202, v58, v0, v46
	ds_read_b128 v[46:49], v206 offset:8192
	v_or_b32_e32 v58, 0xa0, v59
	v_or_b32_e32 v63, 0xc0, v59
	v_add_u32_e32 v204, s41, v202
	v_bitop3_b32 v221, v58, v205, v61 bitop3:0xde
	s_waitcnt lgkmcnt(0)
	v_mfma_f32_32x32x16_bf16 v[2:17], v[42:45], v[134:137], v[2:17]
	v_or_b32_e32 v42, 32, v59
	v_or_b32_e32 v43, 64, v59
	v_or_b32_e32 v44, 0x60, v59
	v_or_b32_e32 v45, 0x80, v59
	v_bitop3_b32 v218, v43, v205, v61 bitop3:0xde
	v_bitop3_b32 v219, v44, v205, v61 bitop3:0xde
	v_bitop3_b32 v220, v45, v205, v61 bitop3:0xde
	s_nop 4
	v_exp_f32_e32 v84, v4
	v_exp_f32_e32 v108, v5
	v_lshl_add_u64 v[4:5], v[40:41], 0, s[38:39]
	global_load_lds_dwordx4 v[4:5], off
	v_lshl_add_u64 v[4:5], v[36:37], 0, s[38:39]
	s_add_i32 m0, s2, 0xe000
	v_mfma_f32_32x32x16_bf16 v[18:33], v[46:49], v[134:137], v[18:33]
	global_load_lds_dwordx4 v[4:5], off
	v_lshl_add_u64 v[4:5], v[38:39], 0, s[16:17]
	s_add_i32 m0, s3, 0x4000
	v_exp_f32_e32 v82, v2
	global_load_lds_dwordx4 v[4:5], off
	v_lshl_add_u64 v[4:5], v[34:35], 0, s[16:17]
	s_add_i32 m0, s3, 0x6000
	s_nop 4
	v_exp_f32_e32 v66, v18
	global_load_lds_dwordx4 v[4:5], off
	v_exp_f32_e32 v106, v3
	v_exp_f32_e32 v0, v19
	v_exp_f32_e32 v68, v20
	v_exp_f32_e32 v110, v21
	v_add_f32_e32 v107, v82, v66
	v_pk_add_f32 v[2:3], v[106:107], v[0:1]
	v_exp_f32_e32 v86, v6
	v_exp_f32_e32 v70, v22
	v_pk_add_f32 v[2:3], v[2:3], v[2:3] op_sel_hi:[0,1]
	v_exp_f32_e32 v112, v7
	v_exp_f32_e32 v114, v23
	v_add_f32_e32 v109, v84, v68
	v_mov_b32_e32 v111, v3
	v_pk_add_f32 v[2:3], v[108:109], v[110:111]
	v_exp_f32_e32 v88, v8
	v_exp_f32_e32 v72, v24
	v_pk_add_f32 v[2:3], v[2:3], v[2:3] op_sel_hi:[0,1]
	v_exp_f32_e32 v116, v9
	v_exp_f32_e32 v118, v25
	v_add_f32_e32 v113, v86, v70
	v_mov_b32_e32 v115, v3
	v_pk_add_f32 v[2:3], v[112:113], v[114:115]
	v_exp_f32_e32 v90, v10
	v_exp_f32_e32 v74, v26
	v_pk_add_f32 v[2:3], v[2:3], v[2:3] op_sel_hi:[0,1]
	v_exp_f32_e32 v120, v11
	v_exp_f32_e32 v122, v27
	v_add_f32_e32 v117, v88, v72
	v_mov_b32_e32 v119, v3
	v_pk_add_f32 v[2:3], v[116:117], v[118:119]
	v_exp_f32_e32 v92, v12
	v_exp_f32_e32 v76, v28
	v_pk_add_f32 v[2:3], v[2:3], v[2:3] op_sel_hi:[0,1]
	v_exp_f32_e32 v124, v13
	v_exp_f32_e32 v126, v29
	v_add_f32_e32 v121, v90, v74
	v_mov_b32_e32 v123, v3
	v_pk_add_f32 v[2:3], v[120:121], v[122:123]
	v_exp_f32_e32 v94, v14
	v_exp_f32_e32 v78, v30
	v_pk_add_f32 v[2:3], v[2:3], v[2:3] op_sel_hi:[0,1]
	v_exp_f32_e32 v128, v15
	v_exp_f32_e32 v184, v31
	v_add_f32_e32 v125, v92, v76
	v_mov_b32_e32 v127, v3
	v_pk_add_f32 v[2:3], v[124:125], v[126:127]
	v_exp_f32_e32 v96, v16
	v_exp_f32_e32 v80, v32
	v_pk_add_f32 v[2:3], v[2:3], v[2:3] op_sel_hi:[0,1]
	v_exp_f32_e32 v186, v17
	v_exp_f32_e32 v188, v33
	v_add_f32_e32 v129, v94, v78
	v_mov_b32_e32 v185, v3
	v_pk_add_f32 v[2:3], v[128:129], v[184:185]
	v_add_f32_e32 v187, v96, v80
	v_pk_add_f32 v[2:3], v[2:3], v[2:3] op_sel_hi:[0,1]
	v_mov_b32_e32 v189, v3
	v_pk_add_f32 v[2:3], v[186:187], v[188:189]
	v_and_b32_e32 v4, 32, v50
	v_pk_add_f32 v[2:3], v[2:3], v[2:3] op_sel:[0,1] op_sel_hi:[1,0]
	s_waitcnt vmcnt(4) lgkmcnt(0)
	s_barrier
	ds_read_b128 v[162:165], v62 offset:24576
	ds_read_b128 v[166:169], v62 offset:16384
	ds_read_b128 v[98:101], v60 offset:24576
	ds_read_b128 v[102:105], v60 offset:16384
	v_mov_b32_e32 v3, v2
	s_nop 1
	v_permlane32_swap_b32_e32 v2, v3
	v_add_f32_e32 v203, v2, v3
	v_or3_b32 v2, v57, v55, s12
	v_lshl_or_b32 v2, v2, 8, s1
	v_or3_b32 v2, v2, v4, v56
	v_ashrrev_i32_e32 v3, 31, v2
	v_lshlrev_b64 v[170:171], 1, v[2:3]
	v_or_b32_e32 v2, s9, v55
	v_or3_b32 v2, v2, s10, v54
	v_lshl_or_b32 v2, v2, 8, s0
	v_or3_b32 v2, v2, v4, v56
	v_ashrrev_i32_e32 v3, 31, v2
	s_add_i32 s0, s11, 0x2000
	v_lshlrev_b32_e32 v4, 8, v51
	v_lshlrev_b64 v[172:173], 1, v[2:3]
	v_or3_b32 v2, s0, v4, v53
	v_ashrrev_i32_e32 v3, 31, v2
	v_lshlrev_b64 v[180:181], 1, v[2:3]
	v_or3_b32 v2, s11, v4, v52
	v_ashrrev_i32_e32 v3, 31, v2
	v_lshlrev_b64 v[182:183], 1, v[2:3]
	v_mov_b32_e32 v2, 0
	v_bitop3_b32 v222, v63, v205, v61 bitop3:0xde
	v_bitop3_b32 v225, v42, v205, v61 bitop3:0xde
	s_mov_b64 s[0:1], s[42:43]
	s_mov_b32 s16, 0x8000
	v_mov_b32_e32 v3, v2
	v_mov_b32_e32 v4, v2
	v_mov_b32_e32 v5, v2
	v_mov_b32_e32 v6, v2
	v_mov_b32_e32 v7, v2
	v_mov_b32_e32 v8, v2
	v_mov_b32_e32 v9, v2
	v_mov_b32_e32 v10, v2
	v_mov_b32_e32 v11, v2
	v_mov_b32_e32 v12, v2
	v_mov_b32_e32 v13, v2
	v_mov_b32_e32 v14, v2
	v_mov_b32_e32 v15, v2
	v_mov_b32_e32 v16, v2
	v_mov_b32_e32 v17, v2
	v_mov_b32_e32 v18, v2
	v_mov_b32_e32 v19, v2
	v_mov_b32_e32 v20, v2
	v_mov_b32_e32 v21, v2
	v_mov_b32_e32 v22, v2
	v_mov_b32_e32 v23, v2
	v_mov_b32_e32 v24, v2
	v_mov_b32_e32 v25, v2
	v_mov_b32_e32 v26, v2
	v_mov_b32_e32 v27, v2
	v_mov_b32_e32 v28, v2
	v_mov_b32_e32 v29, v2
	v_mov_b32_e32 v30, v2
	v_mov_b32_e32 v31, v2
	v_mov_b32_e32 v32, v2
	v_mov_b32_e32 v33, v2
	v_mov_b32_e32 v34, v2
	v_mov_b32_e32 v35, v2
	v_mov_b32_e32 v36, v2
	v_mov_b32_e32 v37, v2
	v_mov_b32_e32 v38, v2
	v_mov_b32_e32 v39, v2
	v_mov_b32_e32 v40, v2
	v_mov_b32_e32 v41, v2
	v_mov_b32_e32 v42, v2
	v_mov_b32_e32 v43, v2
	v_mov_b32_e32 v44, v2
	v_mov_b32_e32 v45, v2
	v_mov_b32_e32 v46, v2
	v_mov_b32_e32 v47, v2
	v_mov_b32_e32 v48, v2
	v_mov_b32_e32 v49, v2
	v_mov_b32_e32 v50, v2
	v_mov_b32_e32 v51, v2
	v_mov_b32_e32 v52, v2
	v_mov_b32_e32 v53, v2
	v_mov_b32_e32 v54, v2
	v_mov_b32_e32 v55, v2
	v_mov_b32_e32 v56, v2
	v_mov_b32_e32 v57, v2
	v_mov_b32_e32 v58, v2
	v_mov_b32_e32 v59, v2
	v_mov_b32_e32 v60, v2
	v_mov_b32_e32 v61, v2
	v_mov_b32_e32 v62, v2
	v_mov_b32_e32 v63, v2
	v_mov_b32_e32 v64, v2
	v_mov_b32_e32 v65, v2
	v_mov_b32_e32 v67, v0
	v_mov_b32_e32 v69, v110
	v_mov_b32_e32 v71, v114
	v_mov_b32_e32 v73, v118
	v_mov_b32_e32 v75, v122
	v_mov_b32_e32 v77, v126
	v_mov_b32_e32 v79, v184
	v_mov_b32_e32 v81, v188
	v_mov_b32_e32 v83, v106
	v_mov_b32_e32 v85, v108
	v_mov_b32_e32 v87, v112
	v_mov_b32_e32 v89, v116
	v_mov_b32_e32 v91, v120
	v_mov_b32_e32 v93, v124
	v_mov_b32_e32 v95, v128
	v_mov_b32_e32 v97, v186
	.p2align	6
